# v61 + P0 weight transposition: the 16 LDS read-backs of an item issued together (one wait instead of 16)
# speedup vs baseline: 1.0024x; 1.0024x over previous
.LBB0_76:
	v_add_u32_e32 v4, 0x400, v3
	s_waitcnt vmcnt(30)
	ds_write2_b32 v3, v44, v45 offset1:66
	s_waitcnt vmcnt(28)
	ds_write2_b32 v3, v46, v48 offset0:132 offset1:198
	s_waitcnt vmcnt(26)
	ds_write2_b32 v4, v47, v49 offset0:8 offset1:74
	s_waitcnt vmcnt(24)
	ds_write2_b32 v4, v50, v51 offset0:140 offset1:206
	v_add_u32_e32 v4, 0x800, v3
	s_waitcnt vmcnt(22)
	ds_write2_b32 v4, v52, v53 offset0:16 offset1:82
	s_waitcnt vmcnt(20)
	ds_write2_b32 v4, v54, v56 offset0:148 offset1:214
	v_add_u32_e32 v4, 0xc00, v3
	s_waitcnt vmcnt(18)
	ds_write2_b32 v4, v55, v57 offset0:24 offset1:90
	s_waitcnt vmcnt(16)
	ds_write2_b32 v4, v58, v59 offset0:156 offset1:222
	v_add_u32_e32 v4, 0x1000, v3
	s_waitcnt vmcnt(14)
	ds_write2_b32 v4, v60, v61 offset0:32 offset1:98
	s_waitcnt vmcnt(12)
	ds_write2_b32 v4, v62, v64 offset0:164 offset1:230
	v_add_u32_e32 v4, 0x1400, v3
	s_waitcnt vmcnt(10)
	ds_write2_b32 v4, v63, v65 offset0:40 offset1:106
	s_waitcnt vmcnt(8)
	ds_write2_b32 v4, v66, v67 offset0:172 offset1:238
	v_add_u32_e32 v4, 0x1800, v3
	s_waitcnt vmcnt(6)
	ds_write2_b32 v4, v68, v69 offset0:48 offset1:114
	s_waitcnt vmcnt(4)
	ds_write2_b32 v4, v70, v72 offset0:180 offset1:246
	v_add_u32_e32 v4, 0x1c00, v3
	s_waitcnt vmcnt(2)
	ds_write2_b32 v4, v71, v73 offset0:56 offset1:122
	s_waitcnt vmcnt(0)
	ds_write2_b32 v4, v74, v75 offset0:188 offset1:254
	s_waitcnt lgkmcnt(0)
	ds_read2_b32 v[100:101], v7 offset1:33
	ds_read2_b32 v[102:103], v7 offset0:66 offset1:99
	ds_read2_b32 v[104:105], v7 offset0:132 offset1:165
	ds_read2_b32 v[106:107], v7 offset0:198 offset1:231
	ds_read2_b32 v[108:109], v7 offset0:8 offset1:41
	ds_read2_b32 v[110:111], v7 offset0:74 offset1:107
	ds_read2_b32 v[112:113], v7 offset0:140 offset1:173
	ds_read2_b32 v[114:115], v7 offset0:206 offset1:239
	ds_read2_b32 v[116:117], v7 offset0:16 offset1:49
	ds_read2_b32 v[118:119], v7 offset0:82 offset1:115
	ds_read2_b32 v[120:121], v7 offset0:148 offset1:181
	ds_read2_b32 v[122:123], v7 offset0:214 offset1:247
	ds_read2_b32 v[124:125], v7 offset0:24 offset1:57
	ds_read2_b32 v[126:127], v7 offset0:90 offset1:123
	ds_read2_b32 v[128:129], v7 offset0:156 offset1:189
	ds_read2_b32 v[130:131], v7 offset0:222 offset1:255
	s_waitcnt lgkmcnt(0)
	s_nop 0
	s_nop 0
	s_nop 0
	v_cvt_pk_bf16_f32 v44, v100, v101
	v_cvt_pk_bf16_f32 v45, v102, v103
	v_cvt_pk_bf16_f32 v46, v104, v105
	v_cvt_pk_bf16_f32 v47, v106, v107
	v_add_u32_e32 v4, s15, v6
	v_ashrrev_i32_e32 v5, 31, v4
	v_mul_lo_u32 v48, s6, v5
	v_mul_lo_u32 v49, s7, v4
	v_mad_u64_u32 v[4:5], s[16:17], s6, v4, 0
	v_add3_u32 v5, v5, v48, v49
	s_ashr_i32 s9, s8, 31
	v_lshl_add_u64 v[4:5], v[4:5], 1, s[2:3]
	s_lshl_b64 s[8:9], s[8:9], 1
	v_lshl_add_u64 v[48:49], v[4:5], 0, s[8:9]
	v_lshlrev_b32_e32 v4, 1, v2
	v_mov_b32_e32 v5, v1
	v_lshl_add_u64 v[48:49], v[48:49], 0, v[4:5]
	global_store_dwordx4 v[48:49], v[44:47], off
	s_nop 1
	s_and_b64 vcc, exec, s[42:43]
	v_cvt_pk_bf16_f32 v44, v108, v109
	v_cvt_pk_bf16_f32 v45, v110, v111
	v_cvt_pk_bf16_f32 v46, v112, v113
	v_cvt_pk_bf16_f32 v47, v114, v115
	v_add_u32_e32 v48, s15, v8
	v_ashrrev_i32_e32 v49, 31, v48
	v_mul_lo_u32 v50, s6, v49
	v_mul_lo_u32 v51, s7, v48
	v_mad_u64_u32 v[48:49], s[16:17], s6, v48, 0
	v_add3_u32 v49, v49, v50, v51
	v_lshl_add_u64 v[48:49], v[48:49], 1, s[2:3]
	v_lshl_add_u64 v[48:49], v[48:49], 0, s[8:9]
	v_lshl_add_u64 v[48:49], v[48:49], 0, v[4:5]
	global_store_dwordx4 v[48:49], v[44:47], off
	s_nop 1
	s_nop 0
	v_cvt_pk_bf16_f32 v44, v116, v117
	v_cvt_pk_bf16_f32 v45, v118, v119
	v_cvt_pk_bf16_f32 v46, v120, v121
	v_cvt_pk_bf16_f32 v47, v122, v123
	v_add_u32_e32 v48, s15, v9
	v_ashrrev_i32_e32 v49, 31, v48
	v_mul_lo_u32 v50, s6, v49
	v_mul_lo_u32 v51, s7, v48
	v_mad_u64_u32 v[48:49], s[16:17], s6, v48, 0
	v_add3_u32 v49, v49, v50, v51
	v_lshl_add_u64 v[48:49], v[48:49], 1, s[2:3]
	v_lshl_add_u64 v[48:49], v[48:49], 0, s[8:9]
	v_lshl_add_u64 v[48:49], v[48:49], 0, v[4:5]
	global_store_dwordx4 v[48:49], v[44:47], off
	s_nop 1
	s_nop 0
	v_cvt_pk_bf16_f32 v44, v124, v125
	v_cvt_pk_bf16_f32 v45, v126, v127
	v_cvt_pk_bf16_f32 v46, v128, v129
	v_cvt_pk_bf16_f32 v47, v130, v131
	v_add_u32_e32 v48, s15, v10
	v_ashrrev_i32_e32 v49, 31, v48
	v_mul_lo_u32 v50, s6, v49
	v_mul_lo_u32 v51, s7, v48
	v_mad_u64_u32 v[48:49], s[6:7], s6, v48, 0
	v_add3_u32 v49, v49, v50, v51
	v_lshl_add_u64 v[48:49], v[48:49], 1, s[2:3]
	v_lshl_add_u64 v[48:49], v[48:49], 0, s[8:9]
	v_lshl_add_u64 v[48:49], v[48:49], 0, v[4:5]
	global_store_dwordx4 v[48:49], v[44:47], off
	s_nop 1
	s_waitcnt lgkmcnt(0)
	s_cbranch_vccnz .LBB0_35
	s_nop 0
	v_add_u32_e32 v44, 0x2000, v3
	ds_write2_b32 v44, v18, v17 offset0:128 offset1:194
	v_add_u32_e32 v44, 0x2400, v3
	ds_write2_b32 v44, v16, v15 offset0:4 offset1:70
	ds_write2_b32 v44, v14, v13 offset0:136 offset1:202
	v_add_u32_e32 v44, 0x2800, v3
	ds_write2_b32 v44, v12, v11 offset0:12 offset1:78
	ds_write2_b32 v44, v27, v26 offset0:144 offset1:210
	v_add_u32_e32 v44, 0x2c00, v3
	ds_write2_b32 v44, v25, v24 offset0:20 offset1:86
	ds_write2_b32 v44, v22, v21 offset0:152 offset1:218
	v_add_u32_e32 v44, 0x3000, v3
	ds_write2_b32 v44, v20, v19 offset0:28 offset1:94
	ds_write2_b32 v44, v35, v34 offset0:160 offset1:226
	v_add_u32_e32 v44, 0x3400, v3
	ds_write2_b32 v44, v33, v32 offset0:36 offset1:102
	ds_write2_b32 v44, v31, v30 offset0:168 offset1:234
	v_add_u32_e32 v44, 0x3800, v3
	ds_write2_b32 v44, v29, v28 offset0:44 offset1:110
	ds_write2_b32 v44, v43, v42 offset0:176 offset1:242
	v_add_u32_e32 v44, 0x3c00, v3
	ds_write2_b32 v44, v41, v40 offset0:52 offset1:118
	ds_write2_b32 v44, v39, v38 offset0:184 offset1:250
	v_add_u32_e32 v44, 0x4000, v3
	ds_write2_b32 v44, v37, v36 offset0:60 offset1:126
	s_waitcnt lgkmcnt(0)
	v_add_u32_e32 v52, 0x2000, v7
	v_add_u32_e32 v53, 0x2400, v7
	ds_read2_b32 v[100:101], v52 offset0:128 offset1:161
	ds_read2_b32 v[102:103], v52 offset0:194 offset1:227
	ds_read2_b32 v[104:105], v53 offset0:4 offset1:37
	ds_read2_b32 v[106:107], v53 offset0:70 offset1:103
	ds_read2_b32 v[108:109], v52 offset0:136 offset1:169
	ds_read2_b32 v[110:111], v52 offset0:202 offset1:235
	ds_read2_b32 v[112:113], v53 offset0:12 offset1:45
	ds_read2_b32 v[114:115], v53 offset0:78 offset1:111
	ds_read2_b32 v[116:117], v52 offset0:144 offset1:177
	ds_read2_b32 v[118:119], v52 offset0:210 offset1:243
	ds_read2_b32 v[120:121], v53 offset0:20 offset1:53
	ds_read2_b32 v[122:123], v53 offset0:86 offset1:119
	ds_read2_b32 v[124:125], v52 offset0:152 offset1:185
	ds_read2_b32 v[126:127], v52 offset0:218 offset1:251
	ds_read2_b32 v[128:129], v53 offset0:28 offset1:61
	ds_read2_b32 v[130:131], v53 offset0:94 offset1:127
	s_waitcnt lgkmcnt(0)
	s_nop 0
	s_nop 0
	s_nop 0
	v_cvt_pk_bf16_f32 v44, v100, v101
	v_cvt_pk_bf16_f32 v45, v102, v103
	v_cvt_pk_bf16_f32 v46, v104, v105
	v_cvt_pk_bf16_f32 v47, v106, v107
	v_add_u32_e32 v48, s20, v6
	v_ashrrev_i32_e32 v49, 31, v48
	v_mul_lo_u32 v50, s12, v49
	v_mul_lo_u32 v51, s13, v48
	v_mad_u64_u32 v[48:49], s[2:3], s12, v48, 0
	v_add3_u32 v49, v49, v50, v51
	s_ashr_i32 s15, s14, 31
	v_lshl_add_u64 v[48:49], v[48:49], 1, s[10:11]
	s_lshl_b64 s[2:3], s[14:15], 1
	v_lshl_add_u64 v[48:49], v[48:49], 0, s[2:3]
	v_lshl_add_u64 v[48:49], v[48:49], 0, v[4:5]
	global_store_dwordx4 v[48:49], v[44:47], off
	s_nop 1
	s_nop 0
	v_cvt_pk_bf16_f32 v44, v108, v109
	v_cvt_pk_bf16_f32 v45, v110, v111
	v_cvt_pk_bf16_f32 v46, v112, v113
	v_cvt_pk_bf16_f32 v47, v114, v115
	v_add_u32_e32 v48, s20, v8
	v_ashrrev_i32_e32 v49, 31, v48
	v_mul_lo_u32 v50, s12, v49
	v_mul_lo_u32 v51, s13, v48
	v_mad_u64_u32 v[48:49], s[6:7], s12, v48, 0
	v_add3_u32 v49, v49, v50, v51
	v_lshl_add_u64 v[48:49], v[48:49], 1, s[10:11]
	v_lshl_add_u64 v[48:49], v[48:49], 0, s[2:3]
	v_lshl_add_u64 v[48:49], v[48:49], 0, v[4:5]
	global_store_dwordx4 v[48:49], v[44:47], off
	s_nop 1
	s_nop 0
	v_cvt_pk_bf16_f32 v44, v116, v117
	v_cvt_pk_bf16_f32 v45, v118, v119
	v_cvt_pk_bf16_f32 v46, v120, v121
	v_cvt_pk_bf16_f32 v47, v122, v123
	v_add_u32_e32 v48, s20, v9
	v_ashrrev_i32_e32 v49, 31, v48
	v_mul_lo_u32 v50, s12, v49
	v_mul_lo_u32 v51, s13, v48
	v_mad_u64_u32 v[48:49], s[6:7], s12, v48, 0
	v_add3_u32 v49, v49, v50, v51
	v_lshl_add_u64 v[48:49], v[48:49], 1, s[10:11]
	v_lshl_add_u64 v[48:49], v[48:49], 0, s[2:3]
	v_lshl_add_u64 v[48:49], v[48:49], 0, v[4:5]
	global_store_dwordx4 v[48:49], v[44:47], off
	s_nop 1
	s_nop 0
	v_cvt_pk_bf16_f32 v44, v124, v125
	v_cvt_pk_bf16_f32 v45, v126, v127
	v_cvt_pk_bf16_f32 v46, v128, v129
	v_cvt_pk_bf16_f32 v47, v130, v131
	v_add_u32_e32 v48, s20, v10
	v_ashrrev_i32_e32 v49, 31, v48
	v_mul_lo_u32 v50, s12, v49
	v_mul_lo_u32 v51, s13, v48
	v_mad_u64_u32 v[48:49], s[6:7], s12, v48, 0
	v_add3_u32 v49, v49, v50, v51
	v_lshl_add_u64 v[48:49], v[48:49], 1, s[10:11]
	v_lshl_add_u64 v[48:49], v[48:49], 0, s[2:3]
	v_lshl_add_u64 v[4:5], v[48:49], 0, v[4:5]
	global_store_dwordx4 v[4:5], v[44:47], off
	s_nop 1
	s_waitcnt lgkmcnt(0)
	s_branch .LBB0_35
